# MLA loop: dropped redundant pre-barrier vmcnt waits (post-barrier wait covers loads; vmcnt(0) kept before the closing barrier)
# baseline (speedup 1.0000x reference)
; #define WAIT_V0() asm volatile("s_waitcnt vmcnt(0)" ::: "memory")
; #define SWRITE(b) do { FRESH_COORDS(); \
;     if constexpr (!KDMA) { _Pragma("unroll") for (int i = 0; i < KC; ++i) *reinterpret_cast<bf16x8*>(shm + (b) * SHM_K + klo[i]) = ks[i]; } \
;     _Pragma("unroll") for (int i = 0; i < VC; ++i) *reinterpret_cast<bf16x8*>(shm + (b) * SHM_V + vlo[i]) = vs[i]; } while (0)
;     ...
;     partialSM<GM>(pB0, pB1, NEEDMASK(kb), kb, L, qpos, hi);
;     __syncthreads(); WAIT_V0(); SWRITE(0);
;     __syncthreads();
.LBB0_371:
	v_mov_b32_e32 v96, v161
	v_ashrrev_i32_e32 v97, 4, v96
	v_and_b32_e32 v99, 0xfffff0, v97
	v_lshlrev_b32_e32 v100, 1, v97
	v_add_u32_e32 v98, 32, v97
	v_and_or_b32 v99, v100, 8, v99
	v_lshrrev_b32_e32 v100, 1, v97
	v_and_b32_e32 v97, 3, v97
	v_and_or_b32 v97, v100, 4, v97
	v_and_b32_e32 v100, 0xfffff0, v98
	v_lshlrev_b32_e32 v98, 1, v98
	v_and_or_b32 v98, v98, 8, v100
	v_lshrrev_b32_e32 v99, 1, v99
	v_bfe_u32 v101, v96, 2, 2
	v_lshrrev_b32_e32 v98, 1, v98
	v_or_b32_e32 v99, v99, v101
	v_lshlrev_b32_e32 v96, 4, v96
	v_or_b32_e32 v98, v98, v101
	v_lshlrev_b32_e32 v99, 9, v99
	v_lshlrev_b32_e32 v97, 6, v97
	v_and_b32_e32 v96, 48, v96
	v_lshlrev_b32_e32 v98, 9, v98
	v_or3_b32 v99, v99, v97, v96
	v_or3_b32 v96, v98, v97, v96
	s_barrier
	s_waitcnt vmcnt(0)
	ds_write_b128 v99, v[112:115]
	ds_write_b128 v96, v[116:119]
	v_exp_f32_e32 v64, v64
	v_exp_f32_e32 v66, v66
	v_exp_f32_e32 v68, v68
	v_exp_f32_e32 v70, v70
	v_exp_f32_e32 v72, v72
	v_exp_f32_e32 v74, v74
	v_exp_f32_e32 v76, v76
	v_exp_f32_e32 v78, v78
	v_exp_f32_e32 v65, v65
	v_exp_f32_e32 v67, v67
	v_exp_f32_e32 v69, v69
	v_exp_f32_e32 v71, v71
	v_exp_f32_e32 v73, v73
	v_exp_f32_e32 v75, v75
	v_exp_f32_e32 v77, v77
	v_exp_f32_e32 v79, v79
	s_waitcnt lgkmcnt(0)
	s_barrier
; #define SBAR() __builtin_amdgcn_sched_barrier(0)
; #define QKT(P0, P1, BUF) qkt<DQK, QL>(P0, P1, shm + K_OFF + (BUF) * SHM_K, qr, qlds, kofs, negM)
;     ...
;     if constexpr (ONEP) { finishSM(pB0, pB1, l_reg, pa0, pa1, pa2, pa3); SBAR(); QKT(pA0, pA1, 0); }
;     else { QKT(pA0, pA1, 0); finishSM(pB0, pB1, l_reg, pa0, pa1, pa2, pa3); }
;     SBAR();
;     if (j + 2 < NT) SLOAD(TKEY(j + 2), 1);
	v_add_f32_e32 v96, 0, v64
	v_add_f32_e32 v96, v65, v96
	v_add_f32_e32 v96, v66, v96
	v_add_f32_e32 v96, v67, v96
	v_add_f32_e32 v96, v68, v96
	v_add_f32_e32 v96, v69, v96
	v_add_f32_e32 v96, v70, v96
	v_add_f32_e32 v96, v71, v96
	v_add_f32_e32 v96, v72, v96
	v_add_f32_e32 v96, v73, v96
	v_add_f32_e32 v96, v74, v96
	v_add_f32_e32 v96, v75, v96
	v_exp_f32_e32 v80, v80
	v_add_f32_e32 v96, v76, v96
	v_exp_f32_e32 v81, v81
	v_add_f32_e32 v96, v77, v96
	v_exp_f32_e32 v82, v82
	v_add_f32_e32 v96, v78, v96
	v_exp_f32_e32 v83, v83
	v_add_f32_e32 v96, v79, v96
	v_exp_f32_e32 v84, v84
	v_add_f32_e32 v96, v80, v96
	v_exp_f32_e32 v85, v85
	v_add_f32_e32 v96, v81, v96
	v_exp_f32_e32 v86, v86
	v_add_f32_e32 v96, v82, v96
	v_exp_f32_e32 v87, v87
	v_add_f32_e32 v96, v83, v96
	v_exp_f32_e32 v88, v88
	v_add_f32_e32 v96, v84, v96
	v_exp_f32_e32 v89, v89
	v_add_f32_e32 v96, v85, v96
	v_exp_f32_e32 v90, v90
	v_add_f32_e32 v96, v86, v96
	v_exp_f32_e32 v91, v91
	v_add_f32_e32 v96, v87, v96
	v_exp_f32_e32 v92, v92
	v_add_f32_e32 v96, v88, v96
	v_exp_f32_e32 v93, v93
	v_add_f32_e32 v96, v89, v96
	v_exp_f32_e32 v94, v94
	v_add_f32_e32 v96, v90, v96
	v_exp_f32_e32 v95, v95
	v_add_f32_e32 v96, v91, v96
	v_add_f32_e32 v96, v92, v96
	v_add_f32_e32 v96, v93, v96
	v_add_f32_e32 v96, v94, v96
	v_add_f32_e32 v179, v95, v96
	v_mov_b32_e32 v180, v179
	v_cvt_pk_bf16_f32 v120, v64, v65
	v_cvt_pk_bf16_f32 v121, v66, v67
	v_cvt_pk_bf16_f32 v122, v68, v69
	v_cvt_pk_bf16_f32 v123, v70, v71
	v_cvt_pk_bf16_f32 v124, v72, v73
	v_cvt_pk_bf16_f32 v125, v74, v75
	v_cvt_pk_bf16_f32 v126, v76, v77
	v_cvt_pk_bf16_f32 v127, v78, v79
	v_cvt_pk_bf16_f32 v142, v80, v81
	v_cvt_pk_bf16_f32 v143, v82, v83
	v_cvt_pk_bf16_f32 v144, v84, v85
	v_cvt_pk_bf16_f32 v145, v86, v87
	v_cvt_pk_bf16_f32 v146, v88, v89
	v_cvt_pk_bf16_f32 v147, v90, v91
	v_cvt_pk_bf16_f32 v148, v92, v93
	v_cvt_pk_bf16_f32 v149, v94, v95
	s_nop 1
	v_permlane32_swap_b32_e32 v179, v180
	v_permlane32_swap_b32_e32 v120, v122
	v_permlane32_swap_b32_e32 v121, v123
	v_permlane32_swap_b32_e32 v124, v126
	v_permlane32_swap_b32_e32 v125, v127
	v_permlane32_swap_b32_e32 v142, v144
	v_permlane32_swap_b32_e32 v143, v145
	v_permlane32_swap_b32_e32 v146, v148
	v_permlane32_swap_b32_e32 v147, v149
	ds_read_b128 v[64:67], v152 offset:32768
	ds_read_b128 v[172:175], v152 offset:45056
	v_mov_b64_e32 v[110:111], s[18:19]
	v_mov_b64_e32 v[108:109], s[16:17]
	v_mov_b64_e32 v[106:107], s[14:15]
	v_mov_b64_e32 v[104:105], s[12:13]
	v_mov_b64_e32 v[102:103], s[10:11]
	v_mov_b64_e32 v[100:101], s[8:9]
	v_mov_b64_e32 v[98:99], s[6:7]
	v_mov_b64_e32 v[96:97], s[4:5]
	s_waitcnt lgkmcnt(1)
	s_nop 0
	v_mfma_f32_32x32x16_bf16 v[80:95], v[64:67], v[138:141], v[96:111]
	s_waitcnt lgkmcnt(0)
	v_mfma_f32_32x32x16_bf16 v[64:79], v[172:175], v[138:141], v[96:111]
	s_nop 6
	ds_read_b128 v[96:99], v156 offset:32768
	ds_read_b128 v[100:103], v156 offset:45056
	s_waitcnt lgkmcnt(1)
	v_mfma_f32_32x32x16_bf16 v[80:95], v[96:99], v[134:137], v[80:95]
	s_waitcnt lgkmcnt(0)
	v_mfma_f32_32x32x16_bf16 v[64:79], v[100:103], v[134:137], v[64:79]
	ds_read_b128 v[96:99], v155 offset:32768
	ds_read_b128 v[100:103], v155 offset:45056
	s_waitcnt lgkmcnt(1)
	v_mfma_f32_32x32x16_bf16 v[80:95], v[96:99], v[130:133], v[80:95]
	s_waitcnt lgkmcnt(0)
	v_mfma_f32_32x32x16_bf16 v[64:79], v[100:103], v[130:133], v[64:79]
	ds_read_b128 v[96:99], v153 offset:32768
	ds_read_b128 v[100:103], v153 offset:45056
	ds_read_b128 v[104:107], v167
	s_waitcnt lgkmcnt(0)
	v_mfma_f32_32x32x16_bf16 v[80:95], v[96:99], v[104:107], v[80:95]
	v_mfma_f32_32x32x16_bf16 v[64:79], v[100:103], v[104:107], v[64:79]
	ds_read_b128 v[96:99], v152 offset:32896
	ds_read_b128 v[100:103], v152 offset:45184
	ds_read_b128 v[104:107], v167 offset:1024
	s_waitcnt lgkmcnt(0)
	v_mfma_f32_32x32x16_bf16 v[80:95], v[96:99], v[104:107], v[80:95]
	v_mfma_f32_32x32x16_bf16 v[64:79], v[100:103], v[104:107], v[64:79]
	ds_read_b128 v[96:99], v156 offset:32896
	ds_read_b128 v[100:103], v156 offset:45184
	ds_read_b128 v[104:107], v167 offset:2048
	s_waitcnt lgkmcnt(0)
	v_mfma_f32_32x32x16_bf16 v[80:95], v[96:99], v[104:107], v[80:95]
	v_mfma_f32_32x32x16_bf16 v[64:79], v[100:103], v[104:107], v[64:79]
	ds_read_b128 v[96:99], v155 offset:32896
	ds_read_b128 v[100:103], v155 offset:45184
	ds_read_b128 v[104:107], v167 offset:3072
	s_waitcnt lgkmcnt(0)
	v_mfma_f32_32x32x16_bf16 v[80:95], v[96:99], v[104:107], v[80:95]
	v_mfma_f32_32x32x16_bf16 v[64:79], v[100:103], v[104:107], v[64:79]
	ds_read_b128 v[96:99], v153 offset:32896
	ds_read_b128 v[100:103], v153 offset:45184
	ds_read_b128 v[104:107], v167 offset:4096
	s_waitcnt lgkmcnt(0)
	v_mfma_f32_32x32x16_bf16 v[80:95], v[96:99], v[104:107], v[80:95]
	v_mfma_f32_32x32x16_bf16 v[64:79], v[100:103], v[104:107], v[64:79]
	ds_read_b128 v[96:99], v152 offset:33024
	ds_read_b128 v[100:103], v152 offset:45312
	ds_read_b128 v[104:107], v167 offset:5120
	s_waitcnt lgkmcnt(0)
	v_mfma_f32_32x32x16_bf16 v[80:95], v[96:99], v[104:107], v[80:95]
	v_mfma_f32_32x32x16_bf16 v[64:79], v[100:103], v[104:107], v[64:79]
	ds_read_b128 v[96:99], v156 offset:33024
	ds_read_b128 v[100:103], v156 offset:45312
	ds_read_b128 v[104:107], v167 offset:6144
	s_waitcnt lgkmcnt(0)
	v_mfma_f32_32x32x16_bf16 v[80:95], v[96:99], v[104:107], v[80:95]
	v_mfma_f32_32x32x16_bf16 v[64:79], v[100:103], v[104:107], v[64:79]
	ds_read_b128 v[96:99], v155 offset:33024
	ds_read_b128 v[100:103], v155 offset:45312
	ds_read_b128 v[104:107], v167 offset:7168
	s_waitcnt lgkmcnt(0)
	v_mfma_f32_32x32x16_bf16 v[80:95], v[96:99], v[104:107], v[80:95]
	v_mfma_f32_32x32x16_bf16 v[64:79], v[100:103], v[104:107], v[64:79]
	ds_read_b128 v[96:99], v153 offset:33024
	ds_read_b128 v[100:103], v153 offset:45312
	ds_read_b128 v[104:107], v167 offset:8192
	s_waitcnt lgkmcnt(0)
	v_mfma_f32_32x32x16_bf16 v[80:95], v[96:99], v[104:107], v[80:95]
	v_mfma_f32_32x32x16_bf16 v[64:79], v[100:103], v[104:107], v[64:79]
	s_cmp_lt_u32 s3, s58
	s_cselect_b64 s[22:23], -1, 0
	s_cmp_ge_u32 s3, s58
	s_cselect_b64 s[20:21], -1, 0
	s_and_b64 vcc, exec, s[20:21]
	s_cbranch_vccnz .LBB0_373
	s_add_u32 s100, s72, s48
	s_addc_u32 s101, s73, s49
	v_readfirstlane_b32 s38, v168
	s_mov_b32 m0, s38
	s_nop 0
	global_load_lds_dwordx4 v235, s[100:101]
	s_add_i32 m0, s38, 0x2000
	s_nop 0
	global_load_lds_dwordx4 v236, s[100:101]
	s_add_i32 m0, s38, 0x4000
	s_nop 0
	global_load_lds_dwordx4 v237, s[100:101]
	s_add_u32 s100, s74, 0xd2bc000
	s_addc_u32 s101, s75, 0
	global_load_dwordx4 v[112:115], v232, s[100:101] offset:256
	s_add_u32 s100, s100, 0x8000
	s_addc_u32 s101, s101, 0
	global_load_dwordx4 v[116:119], v232, s[100:101] offset:256

; #define WAIT_V0() asm volatile("s_waitcnt vmcnt(0)" ::: "memory")
; #define SWRITE(b) do { FRESH_COORDS(); \
;     if constexpr (!KDMA) { _Pragma("unroll") for (int i = 0; i < KC; ++i) *reinterpret_cast<bf16x8*>(shm + (b) * SHM_K + klo[i]) = ks[i]; } \
;     _Pragma("unroll") for (int i = 0; i < VC; ++i) *reinterpret_cast<bf16x8*>(shm + (b) * SHM_V + vlo[i]) = vs[i]; } while (0)
;     ...
;     partialSM<GM>(pA0, pA1, NEEDMASK(kb), kb, L, qpos, hi);
;     __syncthreads();
;     if (j + 2 < NT) { WAIT_V0(); SWRITE(1); }
;     __syncthreads();
;   }
.LBB0_375:
	v_mov_b32_e32 v96, v161
	v_ashrrev_i32_e32 v97, 4, v96
	v_and_b32_e32 v99, 0xfffff0, v97
	v_lshlrev_b32_e32 v100, 1, v97
	v_add_u32_e32 v98, 32, v97
	v_and_or_b32 v99, v100, 8, v99
	v_lshrrev_b32_e32 v100, 1, v97
	v_and_b32_e32 v97, 3, v97
	v_and_or_b32 v97, v100, 4, v97
	v_and_b32_e32 v100, 0xfffff0, v98
	v_lshlrev_b32_e32 v98, 1, v98
	v_and_or_b32 v98, v98, 8, v100
	v_lshrrev_b32_e32 v99, 1, v99
	v_bfe_u32 v101, v96, 2, 2
	v_lshrrev_b32_e32 v98, 1, v98
	v_or_b32_e32 v99, v99, v101
	v_lshlrev_b32_e32 v96, 4, v96
	v_or_b32_e32 v98, v98, v101
	v_lshlrev_b32_e32 v99, 9, v99
	v_lshlrev_b32_e32 v97, 6, v97
	v_and_b32_e32 v96, 48, v96
	v_lshlrev_b32_e32 v98, 9, v98
	v_or3_b32 v99, v99, v97, v96
	v_or3_b32 v96, v98, v97, v96
	s_andn2_b64 vcc, exec, s[22:23]
	s_waitcnt lgkmcnt(0)
	s_barrier
	s_cbranch_vccnz .LBB0_377
	s_waitcnt vmcnt(0)
	ds_write_b128 v99, v[112:115] offset:16384
	ds_write_b128 v96, v[116:119] offset:16384
.LBB0_377:
	s_add_u32 s36, s36, 0x20000
	v_exp_f32_e32 v176, v80
	v_exp_f32_e32 v178, v81
	v_exp_f32_e32 v174, v82
	v_exp_f32_e32 v177, v83
	v_exp_f32_e32 v172, v84
	v_exp_f32_e32 v175, v85
	v_exp_f32_e32 v171, v86
	v_exp_f32_e32 v173, v87
	v_exp_f32_e32 v147, v88
	v_exp_f32_e32 v149, v89
	v_exp_f32_e32 v145, v90
	v_exp_f32_e32 v148, v91
	v_exp_f32_e32 v143, v92
	v_exp_f32_e32 v146, v93
	v_exp_f32_e32 v142, v94
	v_exp_f32_e32 v144, v95
	s_addc_u32 s54, s54, 0
	v_add_f32_e32 v80, v169, v170
	s_add_u32 s55, s55, 0x30000
	v_add_f32_e32 v80, v150, v80
	v_add_f32_e32 v81, v179, v180
	s_addc_u32 s83, s83, 0
	s_add_i32 s22, s3, 2
	s_add_i32 s23, s3, 1
	v_add_f32_e32 v150, v80, v81
	s_cmp_lt_u32 s23, s58
	s_waitcnt vmcnt(0) lgkmcnt(0)
	s_barrier
	s_cbranch_scc0 .LBB0_379
	s_mov_b32 s3, s22
	s_branch .LBB0_369
